# adds: first K-loop iteration of every GEMM unit peeled with srcC=0 on first-touch MFMAs; the 128 per-unit accumulator zeroing moves removed
# speedup vs baseline: 1.0042x; 1.0002x over previous
.LBB0_125:
	s_ashr_i32 s77, s76, 31
	s_lshl_b64 s[18:19], s[76:77], 21
	s_add_u32 s58, s86, s18
	s_addc_u32 s59, s87, s19
	s_and_b64 s[18:19], s[6:7], exec
	s_cselect_b32 s11, s59, s9
	s_cselect_b32 s13, s58, s8
	s_ashr_i32 s17, s16, 31
	s_lshl_b64 s[18:19], s[16:17], 21
	s_add_u32 s36, s96, s18
	s_addc_u32 s37, s97, s19
	s_and_b64 s[18:19], s[6:7], exec
	s_cselect_b32 s17, s37, s15
	s_cselect_b32 s20, s36, s14
	s_add_u32 s8, s8, 0x100080
	s_addc_u32 s9, s9, 0
	s_add_u32 s21, s14, 0x100
	s_addc_u32 s28, s15, 0
	s_mov_b32 s29, -2
	ds_read_b128 v[130:133], v176
	ds_read_b128 v[134:137], v176 offset:1024
	ds_read_b128 v[170:173], v176 offset:2048
	ds_read_b128 v[180:183], v176 offset:3072
	ds_read_b128 v[184:187], v177
	ds_read_b128 v[188:191], v177 offset:1024
	ds_read_b128 v[192:195], v177 offset:2048
	ds_read_b128 v[198:201], v177 offset:3072
	s_add_u32 s14, s8, 0xfff00080
	s_addc_u32 s15, s9, -1
	s_cmp_eq_u32 s29, 60
	s_cselect_b32 s19, s11, s15
	s_cselect_b32 s18, s13, s14
	s_cselect_b32 s15, s17, s28
	s_cselect_b32 s14, s20, s21
	s_add_i32 m0, s73, 0xc000
	ds_read_b128 v[202:205], v178
	ds_read_b128 v[206:209], v178 offset:1024
	ds_read_b128 v[210:213], v178 offset:2048
	ds_read_b128 v[214:217], v178 offset:3072
	ds_read_b128 v[218:221], v178 offset:4096
	ds_read_b128 v[222:225], v178 offset:5120
	ds_read_b128 v[226:229], v178 offset:6144
	ds_read_b128 v[230:233], v178 offset:7168
	global_load_lds_dwordx4 v160, s[8:9]
	s_add_i32 m0, s73, 0xe000
	s_nop 0
	global_load_lds_dwordx4 v162, s[8:9]
	s_waitcnt vmcnt(8)
	s_waitcnt lgkmcnt(0)
	s_setprio 1
	s_barrier
	v_mfma_f32_16x16x32_bf16 v[126:129], v[130:133], v[202:205], 0
	v_mfma_f32_16x16x32_bf16 v[122:125], v[170:173], v[202:205], 0
	v_mfma_f32_16x16x32_bf16 v[110:113], v[130:133], v[210:213], 0
	v_mfma_f32_16x16x32_bf16 v[106:109], v[170:173], v[210:213], 0
	v_mfma_f32_16x16x32_bf16 v[94:97], v[130:133], v[218:221], 0
	v_mfma_f32_16x16x32_bf16 v[90:93], v[170:173], v[218:221], 0
	v_mfma_f32_16x16x32_bf16 v[78:81], v[130:133], v[226:229], 0
	v_mfma_f32_16x16x32_bf16 v[74:77], v[170:173], v[226:229], 0
	v_mfma_f32_16x16x32_bf16 v[126:129], v[134:137], v[206:209], v[126:129]
	v_mfma_f32_16x16x32_bf16 v[122:125], v[180:183], v[206:209], v[122:125]
	v_mfma_f32_16x16x32_bf16 v[110:113], v[134:137], v[214:217], v[110:113]
	v_mfma_f32_16x16x32_bf16 v[106:109], v[180:183], v[214:217], v[106:109]
	v_mfma_f32_16x16x32_bf16 v[94:97], v[134:137], v[222:225], v[94:97]
	v_mfma_f32_16x16x32_bf16 v[90:93], v[180:183], v[222:225], v[90:93]
	v_mfma_f32_16x16x32_bf16 v[78:81], v[134:137], v[230:233], v[78:81]
	v_mfma_f32_16x16x32_bf16 v[74:77], v[180:183], v[230:233], v[74:77]
	v_mfma_f32_16x16x32_bf16 v[118:121], v[184:187], v[202:205], 0
	v_mfma_f32_16x16x32_bf16 v[114:117], v[192:195], v[202:205], 0
	v_mfma_f32_16x16x32_bf16 v[102:105], v[184:187], v[210:213], 0
	v_mfma_f32_16x16x32_bf16 v[98:101], v[192:195], v[210:213], 0
	v_mfma_f32_16x16x32_bf16 v[86:89], v[184:187], v[218:221], 0
	v_mfma_f32_16x16x32_bf16 v[82:85], v[192:195], v[218:221], 0
	v_mfma_f32_16x16x32_bf16 v[70:73], v[184:187], v[226:229], 0
	v_mfma_f32_16x16x32_bf16 v[66:69], v[192:195], v[226:229], 0
	v_mfma_f32_16x16x32_bf16 v[118:121], v[188:191], v[206:209], v[118:121]
	v_mfma_f32_16x16x32_bf16 v[114:117], v[198:201], v[206:209], v[114:117]
	v_mfma_f32_16x16x32_bf16 v[102:105], v[188:191], v[214:217], v[102:105]
	v_mfma_f32_16x16x32_bf16 v[98:101], v[198:201], v[214:217], v[98:101]
	v_mfma_f32_16x16x32_bf16 v[86:89], v[188:191], v[222:225], v[86:89]
	v_mfma_f32_16x16x32_bf16 v[82:85], v[198:201], v[222:225], v[82:85]
	v_mfma_f32_16x16x32_bf16 v[70:73], v[188:191], v[230:233], v[70:73]
	v_mfma_f32_16x16x32_bf16 v[66:69], v[198:201], v[230:233], v[66:69]
	s_barrier
	s_setprio 0
	s_add_i32 s30, s69, s35
	s_mov_b32 m0, s30
	ds_read_b128 v[202:205], v178 offset:16384
	ds_read_b128 v[206:209], v178 offset:17408
	ds_read_b128 v[210:213], v178 offset:18432
	ds_read_b128 v[214:217], v178 offset:19456
	ds_read_b128 v[218:221], v178 offset:20480
	ds_read_b128 v[222:225], v178 offset:21504
	ds_read_b128 v[226:229], v178 offset:22528
	ds_read_b128 v[230:233], v178 offset:23552
	global_load_lds_dwordx4 v140, s[14:15]
	s_add_i32 m0, s30, 0x2000
	s_add_u32 s30, s14, 0x100000
	s_addc_u32 s31, s15, 0
	s_add_i32 s38, s70, s35
	global_load_lds_dwordx4 v144, s[14:15]
	s_mov_b32 m0, s38
	global_load_lds_dwordx4 v140, s[30:31]
	s_add_i32 m0, s38, 0x2000
	s_nop 0
	global_load_lds_dwordx4 v144, s[30:31]
	s_mov_b32 m0, s73
	s_nop 0
	global_load_lds_dwordx4 v138, s[18:19]
	s_mov_b32 m0, s66
	s_nop 0
	global_load_lds_dwordx4 v142, s[18:19]
	s_waitcnt vmcnt(8)
	s_waitcnt lgkmcnt(0)
	s_setprio 1
	s_barrier
	v_mfma_f32_16x16x32_bf16 v[62:65], v[130:133], v[202:205], 0
	v_mfma_f32_16x16x32_bf16 v[58:61], v[170:173], v[202:205], 0
	v_mfma_f32_16x16x32_bf16 v[46:49], v[130:133], v[210:213], 0
	v_mfma_f32_16x16x32_bf16 v[42:45], v[170:173], v[210:213], 0
	v_mfma_f32_16x16x32_bf16 v[30:33], v[130:133], v[218:221], 0
	v_mfma_f32_16x16x32_bf16 v[26:29], v[170:173], v[218:221], 0
	v_mfma_f32_16x16x32_bf16 v[14:17], v[130:133], v[226:229], 0
	v_mfma_f32_16x16x32_bf16 v[10:13], v[170:173], v[226:229], 0
	v_mfma_f32_16x16x32_bf16 v[62:65], v[134:137], v[206:209], v[62:65]
	v_mfma_f32_16x16x32_bf16 v[58:61], v[180:183], v[206:209], v[58:61]
	v_mfma_f32_16x16x32_bf16 v[46:49], v[134:137], v[214:217], v[46:49]
	v_mfma_f32_16x16x32_bf16 v[42:45], v[180:183], v[214:217], v[42:45]
	v_mfma_f32_16x16x32_bf16 v[30:33], v[134:137], v[222:225], v[30:33]
	v_mfma_f32_16x16x32_bf16 v[26:29], v[180:183], v[222:225], v[26:29]
	v_mfma_f32_16x16x32_bf16 v[14:17], v[134:137], v[230:233], v[14:17]
	v_mfma_f32_16x16x32_bf16 v[10:13], v[180:183], v[230:233], v[10:13]
	v_mfma_f32_16x16x32_bf16 v[54:57], v[184:187], v[202:205], 0
	v_mfma_f32_16x16x32_bf16 v[50:53], v[192:195], v[202:205], 0
	v_mfma_f32_16x16x32_bf16 v[38:41], v[184:187], v[210:213], 0
	v_mfma_f32_16x16x32_bf16 v[34:37], v[192:195], v[210:213], 0
	v_mfma_f32_16x16x32_bf16 v[22:25], v[184:187], v[218:221], 0
	v_mfma_f32_16x16x32_bf16 v[18:21], v[192:195], v[218:221], 0
	v_mfma_f32_16x16x32_bf16 v[6:9], v[184:187], v[226:229], 0
	v_mfma_f32_16x16x32_bf16 v[2:5], v[192:195], v[226:229], 0
	v_mfma_f32_16x16x32_bf16 v[54:57], v[188:191], v[206:209], v[54:57]
	v_mfma_f32_16x16x32_bf16 v[50:53], v[198:201], v[206:209], v[50:53]
	v_mfma_f32_16x16x32_bf16 v[38:41], v[188:191], v[214:217], v[38:41]
	v_mfma_f32_16x16x32_bf16 v[34:37], v[198:201], v[214:217], v[34:37]
	v_mfma_f32_16x16x32_bf16 v[22:25], v[188:191], v[222:225], v[22:25]
	v_mfma_f32_16x16x32_bf16 v[18:21], v[198:201], v[222:225], v[18:21]
	v_mfma_f32_16x16x32_bf16 v[6:9], v[188:191], v[230:233], v[6:9]
	v_mfma_f32_16x16x32_bf16 v[2:5], v[198:201], v[230:233], v[2:5]
	s_barrier
	s_setprio 0
	s_add_i32 s30, 0, 0x18000
	v_add_u32_e32 v146, s30, v155
	s_add_i32 s31, 0, 0x1c000
	ds_read_b128 v[130:133], v146
	ds_read_b128 v[134:137], v146 offset:1024
	ds_read_b128 v[170:173], v146 offset:2048
	ds_read_b128 v[180:183], v146 offset:3072
	v_add_u32_e32 v146, s31, v155
	ds_read_b128 v[184:187], v146
	ds_read_b128 v[188:191], v146 offset:1024
	ds_read_b128 v[192:195], v146 offset:2048
	ds_read_b128 v[198:201], v146 offset:3072
	s_add_u32 s18, s18, 0x100000
	s_addc_u32 s19, s19, 0
	s_mov_b32 m0, s67
	ds_read_b128 v[202:205], v178 offset:32768
	ds_read_b128 v[206:209], v178 offset:33792
	ds_read_b128 v[210:213], v178 offset:34816
	ds_read_b128 v[214:217], v178 offset:35840
	ds_read_b128 v[218:221], v178 offset:36864
	ds_read_b128 v[222:225], v178 offset:37888
	ds_read_b128 v[226:229], v178 offset:38912
	ds_read_b128 v[230:233], v178 offset:39936
	global_load_lds_dwordx4 v138, s[18:19]
	s_mov_b32 m0, s88
	s_nop 0
	global_load_lds_dwordx4 v142, s[18:19]
	s_waitcnt vmcnt(8)
	s_waitcnt lgkmcnt(0)
	s_setprio 1
	s_barrier
	v_mfma_f32_16x16x32_bf16 v[126:129], v[130:133], v[202:205], v[126:129]
	v_mfma_f32_16x16x32_bf16 v[122:125], v[170:173], v[202:205], v[122:125]
	v_mfma_f32_16x16x32_bf16 v[110:113], v[130:133], v[210:213], v[110:113]
	v_mfma_f32_16x16x32_bf16 v[106:109], v[170:173], v[210:213], v[106:109]
	v_mfma_f32_16x16x32_bf16 v[94:97], v[130:133], v[218:221], v[94:97]
	v_mfma_f32_16x16x32_bf16 v[90:93], v[170:173], v[218:221], v[90:93]
	v_mfma_f32_16x16x32_bf16 v[78:81], v[130:133], v[226:229], v[78:81]
	v_mfma_f32_16x16x32_bf16 v[74:77], v[170:173], v[226:229], v[74:77]
	v_mfma_f32_16x16x32_bf16 v[126:129], v[134:137], v[206:209], v[126:129]
	v_mfma_f32_16x16x32_bf16 v[122:125], v[180:183], v[206:209], v[122:125]
	v_mfma_f32_16x16x32_bf16 v[110:113], v[134:137], v[214:217], v[110:113]
	v_mfma_f32_16x16x32_bf16 v[106:109], v[180:183], v[214:217], v[106:109]
	v_mfma_f32_16x16x32_bf16 v[94:97], v[134:137], v[222:225], v[94:97]
	v_mfma_f32_16x16x32_bf16 v[90:93], v[180:183], v[222:225], v[90:93]
	v_mfma_f32_16x16x32_bf16 v[78:81], v[134:137], v[230:233], v[78:81]
	v_mfma_f32_16x16x32_bf16 v[74:77], v[180:183], v[230:233], v[74:77]
	v_mfma_f32_16x16x32_bf16 v[118:121], v[184:187], v[202:205], v[118:121]
	v_mfma_f32_16x16x32_bf16 v[114:117], v[192:195], v[202:205], v[114:117]
	v_mfma_f32_16x16x32_bf16 v[102:105], v[184:187], v[210:213], v[102:105]
	v_mfma_f32_16x16x32_bf16 v[98:101], v[192:195], v[210:213], v[98:101]
	v_mfma_f32_16x16x32_bf16 v[86:89], v[184:187], v[218:221], v[86:89]
	v_mfma_f32_16x16x32_bf16 v[82:85], v[192:195], v[218:221], v[82:85]
	v_mfma_f32_16x16x32_bf16 v[70:73], v[184:187], v[226:229], v[70:73]
	v_mfma_f32_16x16x32_bf16 v[66:69], v[192:195], v[226:229], v[66:69]
	v_mfma_f32_16x16x32_bf16 v[118:121], v[188:191], v[206:209], v[118:121]
	v_mfma_f32_16x16x32_bf16 v[114:117], v[198:201], v[206:209], v[114:117]
	v_mfma_f32_16x16x32_bf16 v[102:105], v[188:191], v[214:217], v[102:105]
	v_mfma_f32_16x16x32_bf16 v[98:101], v[198:201], v[214:217], v[98:101]
	v_mfma_f32_16x16x32_bf16 v[86:89], v[188:191], v[222:225], v[86:89]
	v_mfma_f32_16x16x32_bf16 v[82:85], v[198:201], v[222:225], v[82:85]
	v_mfma_f32_16x16x32_bf16 v[70:73], v[188:191], v[230:233], v[70:73]
	v_mfma_f32_16x16x32_bf16 v[66:69], v[198:201], v[230:233], v[66:69]
	s_barrier
	s_setprio 0
	s_add_u32 s14, s14, 0x80
	s_addc_u32 s15, s15, 0
	s_add_i32 m0, s35, 0x18000
	ds_read_b128 v[202:205], v178 offset:49152
	ds_read_b128 v[206:209], v178 offset:50176
	ds_read_b128 v[210:213], v178 offset:51200
	ds_read_b128 v[214:217], v178 offset:52224
	ds_read_b128 v[218:221], v178 offset:53248
	ds_read_b128 v[222:225], v178 offset:54272
	ds_read_b128 v[226:229], v178 offset:55296
	ds_read_b128 v[230:233], v178 offset:56320
	global_load_lds_dwordx4 v140, s[14:15]
	s_add_i32 m0, s35, 0x1a000
	s_add_u32 s18, s18, 0xfff00080
	global_load_lds_dwordx4 v144, s[14:15]
	s_addc_u32 s19, s19, -1
	s_add_u32 s14, s14, 0x100000
	s_addc_u32 s15, s15, 0
	s_add_i32 m0, s35, 0x1c000
	s_nop 0
	global_load_lds_dwordx4 v140, s[14:15]
	s_add_i32 m0, s35, 0x1e000
	s_nop 0
	global_load_lds_dwordx4 v144, s[14:15]
	s_mov_b32 m0, s89
	s_nop 0
	global_load_lds_dwordx4 v138, s[18:19]
	s_mov_b32 m0, s68
	s_nop 0
	global_load_lds_dwordx4 v142, s[18:19]
	s_waitcnt vmcnt(8)
	s_waitcnt lgkmcnt(0)
	s_setprio 1
	s_barrier
	v_mfma_f32_16x16x32_bf16 v[62:65], v[130:133], v[202:205], v[62:65]
	v_mfma_f32_16x16x32_bf16 v[58:61], v[170:173], v[202:205], v[58:61]
	v_mfma_f32_16x16x32_bf16 v[46:49], v[130:133], v[210:213], v[46:49]
	v_mfma_f32_16x16x32_bf16 v[42:45], v[170:173], v[210:213], v[42:45]
	v_mfma_f32_16x16x32_bf16 v[30:33], v[130:133], v[218:221], v[30:33]
	v_mfma_f32_16x16x32_bf16 v[26:29], v[170:173], v[218:221], v[26:29]
	v_mfma_f32_16x16x32_bf16 v[14:17], v[130:133], v[226:229], v[14:17]
	v_mfma_f32_16x16x32_bf16 v[10:13], v[170:173], v[226:229], v[10:13]
	v_mfma_f32_16x16x32_bf16 v[62:65], v[134:137], v[206:209], v[62:65]
	v_mfma_f32_16x16x32_bf16 v[58:61], v[180:183], v[206:209], v[58:61]
	v_mfma_f32_16x16x32_bf16 v[46:49], v[134:137], v[214:217], v[46:49]
	v_mfma_f32_16x16x32_bf16 v[42:45], v[180:183], v[214:217], v[42:45]
	v_mfma_f32_16x16x32_bf16 v[30:33], v[134:137], v[222:225], v[30:33]
	v_mfma_f32_16x16x32_bf16 v[26:29], v[180:183], v[222:225], v[26:29]
	v_mfma_f32_16x16x32_bf16 v[14:17], v[134:137], v[230:233], v[14:17]
	v_mfma_f32_16x16x32_bf16 v[10:13], v[180:183], v[230:233], v[10:13]
	v_mfma_f32_16x16x32_bf16 v[54:57], v[184:187], v[202:205], v[54:57]
	v_mfma_f32_16x16x32_bf16 v[50:53], v[192:195], v[202:205], v[50:53]
	v_mfma_f32_16x16x32_bf16 v[38:41], v[184:187], v[210:213], v[38:41]
	v_mfma_f32_16x16x32_bf16 v[34:37], v[192:195], v[210:213], v[34:37]
	v_mfma_f32_16x16x32_bf16 v[22:25], v[184:187], v[218:221], v[22:25]
	v_mfma_f32_16x16x32_bf16 v[18:21], v[192:195], v[218:221], v[18:21]
	v_mfma_f32_16x16x32_bf16 v[6:9], v[184:187], v[226:229], v[6:9]
	v_mfma_f32_16x16x32_bf16 v[2:5], v[192:195], v[226:229], v[2:5]
	v_mfma_f32_16x16x32_bf16 v[54:57], v[188:191], v[206:209], v[54:57]
	v_mfma_f32_16x16x32_bf16 v[50:53], v[198:201], v[206:209], v[50:53]
	v_mfma_f32_16x16x32_bf16 v[38:41], v[188:191], v[214:217], v[38:41]
	v_mfma_f32_16x16x32_bf16 v[34:37], v[198:201], v[214:217], v[34:37]
	v_mfma_f32_16x16x32_bf16 v[22:25], v[188:191], v[222:225], v[22:25]
	v_mfma_f32_16x16x32_bf16 v[18:21], v[198:201], v[222:225], v[18:21]
	v_mfma_f32_16x16x32_bf16 v[6:9], v[188:191], v[230:233], v[6:9]
	v_mfma_f32_16x16x32_bf16 v[2:5], v[198:201], v[230:233], v[2:5]
	s_barrier
	s_setprio 0
	s_add_i32 s29, s29, 2
	s_add_u32 s8, s8, 0x100
	s_addc_u32 s9, s9, 0
	s_add_u32 s21, s21, 0x100
	s_addc_u32 s28, s28, 0
	s_cmp_gt_u32 s29, 61

.LBB0_677:
	s_ashr_i32 s47, s46, 31
	s_lshl_b64 s[48:49], s[46:47], 21
	s_add_u32 s48, s86, s48
	s_addc_u32 s49, s87, s49
	s_and_b64 s[50:51], s[4:5], exec
	s_cselect_b32 s7, s49, s59
	s_cselect_b32 s47, s48, s58
	s_ashr_i32 s45, s44, 31
	s_lshl_b64 s[50:51], s[44:45], 21
	s_add_u32 s50, s82, s50
	s_addc_u32 s51, s83, s51
	s_and_b64 s[62:63], s[4:5], exec
	s_cselect_b32 s45, s51, s61
	s_cselect_b32 s57, s50, s60
	s_add_u32 s58, s58, 0x100080
	s_addc_u32 s59, s59, 0
	s_add_u32 s76, s60, 0x100
	s_addc_u32 s77, s61, 0
	s_mov_b32 s78, -2
	s_waitcnt lgkmcnt(0)
	ds_read_b128 v[148:151], v159
	ds_read_b128 v[152:155], v159 offset:1024
	ds_read_b128 v[164:167], v159 offset:2048
	ds_read_b128 v[168:171], v159 offset:3072
	ds_read_b128 v[172:175], v160
	ds_read_b128 v[176:179], v160 offset:1024
	ds_read_b128 v[180:183], v160 offset:2048
	ds_read_b128 v[184:187], v160 offset:3072
	s_add_u32 s60, s58, 0xfff00080
	s_addc_u32 s61, s59, -1
	s_cmp_eq_u32 s78, 60
	s_cselect_b32 s63, s7, s61
	s_cselect_b32 s62, s47, s60
	s_cselect_b32 s61, s45, s77
	s_cselect_b32 s60, s57, s76
	s_add_i32 m0, s64, 0xc000
	ds_read_b128 v[188:191], v161
	ds_read_b128 v[192:195], v161 offset:1024
	ds_read_b128 v[198:201], v161 offset:2048
	ds_read_b128 v[202:205], v161 offset:3072
	ds_read_b128 v[206:209], v161 offset:4096
	ds_read_b128 v[210:213], v161 offset:5120
	ds_read_b128 v[214:217], v161 offset:6144
	ds_read_b128 v[218:221], v161 offset:7168
	global_load_lds_dwordx4 v140, s[58:59]
	s_add_i32 m0, s64, 0xe000
	s_nop 0
	global_load_lds_dwordx4 v142, s[58:59]
	s_waitcnt vmcnt(8)
	s_waitcnt lgkmcnt(0)
	s_setprio 1
	s_barrier
	v_mfma_f32_16x16x32_bf16 v[126:129], v[148:151], v[188:191], 0
	v_mfma_f32_16x16x32_bf16 v[122:125], v[164:167], v[188:191], 0
	v_mfma_f32_16x16x32_bf16 v[110:113], v[148:151], v[198:201], 0
	v_mfma_f32_16x16x32_bf16 v[106:109], v[164:167], v[198:201], 0
	v_mfma_f32_16x16x32_bf16 v[94:97], v[148:151], v[206:209], 0
	v_mfma_f32_16x16x32_bf16 v[90:93], v[164:167], v[206:209], 0
	v_mfma_f32_16x16x32_bf16 v[78:81], v[148:151], v[214:217], 0
	v_mfma_f32_16x16x32_bf16 v[74:77], v[164:167], v[214:217], 0
	v_mfma_f32_16x16x32_bf16 v[126:129], v[152:155], v[192:195], v[126:129]
	v_mfma_f32_16x16x32_bf16 v[122:125], v[168:171], v[192:195], v[122:125]
	v_mfma_f32_16x16x32_bf16 v[110:113], v[152:155], v[202:205], v[110:113]
	v_mfma_f32_16x16x32_bf16 v[106:109], v[168:171], v[202:205], v[106:109]
	v_mfma_f32_16x16x32_bf16 v[94:97], v[152:155], v[210:213], v[94:97]
	v_mfma_f32_16x16x32_bf16 v[90:93], v[168:171], v[210:213], v[90:93]
	v_mfma_f32_16x16x32_bf16 v[78:81], v[152:155], v[218:221], v[78:81]
	v_mfma_f32_16x16x32_bf16 v[74:77], v[168:171], v[218:221], v[74:77]
	v_mfma_f32_16x16x32_bf16 v[118:121], v[172:175], v[188:191], 0
	v_mfma_f32_16x16x32_bf16 v[114:117], v[180:183], v[188:191], 0
	v_mfma_f32_16x16x32_bf16 v[102:105], v[172:175], v[198:201], 0
	v_mfma_f32_16x16x32_bf16 v[98:101], v[180:183], v[198:201], 0
	v_mfma_f32_16x16x32_bf16 v[86:89], v[172:175], v[206:209], 0
	v_mfma_f32_16x16x32_bf16 v[82:85], v[180:183], v[206:209], 0
	v_mfma_f32_16x16x32_bf16 v[70:73], v[172:175], v[214:217], 0
	v_mfma_f32_16x16x32_bf16 v[66:69], v[180:183], v[214:217], 0
	v_mfma_f32_16x16x32_bf16 v[118:121], v[176:179], v[192:195], v[118:121]
	v_mfma_f32_16x16x32_bf16 v[114:117], v[184:187], v[192:195], v[114:117]
	v_mfma_f32_16x16x32_bf16 v[102:105], v[176:179], v[202:205], v[102:105]
	v_mfma_f32_16x16x32_bf16 v[98:101], v[184:187], v[202:205], v[98:101]
	v_mfma_f32_16x16x32_bf16 v[86:89], v[176:179], v[210:213], v[86:89]
	v_mfma_f32_16x16x32_bf16 v[82:85], v[184:187], v[210:213], v[82:85]
	v_mfma_f32_16x16x32_bf16 v[70:73], v[176:179], v[218:221], v[70:73]
	v_mfma_f32_16x16x32_bf16 v[66:69], v[184:187], v[218:221], v[66:69]
	s_barrier
	s_setprio 0
	s_add_i32 s79, s74, s33
	s_mov_b32 m0, s79
	ds_read_b128 v[188:191], v161 offset:16384
	ds_read_b128 v[192:195], v161 offset:17408
	ds_read_b128 v[198:201], v161 offset:18432
	ds_read_b128 v[202:205], v161 offset:19456
	ds_read_b128 v[206:209], v161 offset:20480
	ds_read_b128 v[210:213], v161 offset:21504
	ds_read_b128 v[214:217], v161 offset:22528
	ds_read_b128 v[218:221], v161 offset:23552
	global_load_lds_dwordx4 v132, s[60:61]
	s_add_i32 m0, s79, 0x2000
	s_add_u32 s80, s60, 0x100000
	s_addc_u32 s81, s61, 0
	s_add_i32 s79, s75, s33
	global_load_lds_dwordx4 v136, s[60:61]
	s_mov_b32 m0, s79
	global_load_lds_dwordx4 v132, s[80:81]
	s_add_i32 m0, s79, 0x2000
	s_nop 0
	global_load_lds_dwordx4 v136, s[80:81]
	s_mov_b32 m0, s64
	s_nop 0
	global_load_lds_dwordx4 v130, s[62:63]
	s_mov_b32 m0, s65
	s_nop 0
	global_load_lds_dwordx4 v134, s[62:63]
	s_waitcnt vmcnt(8)
	s_waitcnt lgkmcnt(0)
	s_setprio 1
	s_barrier
	v_mfma_f32_16x16x32_bf16 v[62:65], v[148:151], v[188:191], 0
	v_mfma_f32_16x16x32_bf16 v[58:61], v[164:167], v[188:191], 0
	v_mfma_f32_16x16x32_bf16 v[46:49], v[148:151], v[198:201], 0
	v_mfma_f32_16x16x32_bf16 v[42:45], v[164:167], v[198:201], 0
	v_mfma_f32_16x16x32_bf16 v[30:33], v[148:151], v[206:209], 0
	v_mfma_f32_16x16x32_bf16 v[26:29], v[164:167], v[206:209], 0
	v_mfma_f32_16x16x32_bf16 v[14:17], v[148:151], v[214:217], 0
	v_mfma_f32_16x16x32_bf16 v[10:13], v[164:167], v[214:217], 0
	v_mfma_f32_16x16x32_bf16 v[62:65], v[152:155], v[192:195], v[62:65]
	v_mfma_f32_16x16x32_bf16 v[58:61], v[168:171], v[192:195], v[58:61]
	v_mfma_f32_16x16x32_bf16 v[46:49], v[152:155], v[202:205], v[46:49]
	v_mfma_f32_16x16x32_bf16 v[42:45], v[168:171], v[202:205], v[42:45]
	v_mfma_f32_16x16x32_bf16 v[30:33], v[152:155], v[210:213], v[30:33]
	v_mfma_f32_16x16x32_bf16 v[26:29], v[168:171], v[210:213], v[26:29]
	v_mfma_f32_16x16x32_bf16 v[14:17], v[152:155], v[218:221], v[14:17]
	v_mfma_f32_16x16x32_bf16 v[10:13], v[168:171], v[218:221], v[10:13]
	v_mfma_f32_16x16x32_bf16 v[54:57], v[172:175], v[188:191], 0
	v_mfma_f32_16x16x32_bf16 v[50:53], v[180:183], v[188:191], 0
	v_mfma_f32_16x16x32_bf16 v[38:41], v[172:175], v[198:201], 0
	v_mfma_f32_16x16x32_bf16 v[34:37], v[180:183], v[198:201], 0
	v_mfma_f32_16x16x32_bf16 v[22:25], v[172:175], v[206:209], 0
	v_mfma_f32_16x16x32_bf16 v[18:21], v[180:183], v[206:209], 0
	v_mfma_f32_16x16x32_bf16 v[6:9], v[172:175], v[214:217], 0
	v_mfma_f32_16x16x32_bf16 v[2:5], v[180:183], v[214:217], 0
	v_mfma_f32_16x16x32_bf16 v[54:57], v[176:179], v[192:195], v[54:57]
	v_mfma_f32_16x16x32_bf16 v[50:53], v[184:187], v[192:195], v[50:53]
	v_mfma_f32_16x16x32_bf16 v[38:41], v[176:179], v[202:205], v[38:41]
	v_mfma_f32_16x16x32_bf16 v[34:37], v[184:187], v[202:205], v[34:37]
	v_mfma_f32_16x16x32_bf16 v[22:25], v[176:179], v[210:213], v[22:25]
	v_mfma_f32_16x16x32_bf16 v[18:21], v[184:187], v[210:213], v[18:21]
	v_mfma_f32_16x16x32_bf16 v[6:9], v[176:179], v[218:221], v[6:9]
	v_mfma_f32_16x16x32_bf16 v[2:5], v[184:187], v[218:221], v[2:5]
	s_barrier
	s_setprio 0
	s_add_i32 s79, 0, 0x18000
	v_add_u32_e32 v138, s79, v157
	s_add_i32 s80, 0, 0x1c000
	ds_read_b128 v[148:151], v138
	ds_read_b128 v[152:155], v138 offset:1024
	ds_read_b128 v[164:167], v138 offset:2048
	ds_read_b128 v[168:171], v138 offset:3072
	v_add_u32_e32 v138, s80, v157
	ds_read_b128 v[172:175], v138
	ds_read_b128 v[176:179], v138 offset:1024
	ds_read_b128 v[180:183], v138 offset:2048
	ds_read_b128 v[184:187], v138 offset:3072
	s_add_u32 s62, s62, 0x100000
	s_addc_u32 s63, s63, 0
	s_mov_b32 m0, s66
	ds_read_b128 v[188:191], v161 offset:32768
	ds_read_b128 v[192:195], v161 offset:33792
	ds_read_b128 v[198:201], v161 offset:34816
	ds_read_b128 v[202:205], v161 offset:35840
	ds_read_b128 v[206:209], v161 offset:36864
	ds_read_b128 v[210:213], v161 offset:37888
	ds_read_b128 v[214:217], v161 offset:38912
	ds_read_b128 v[218:221], v161 offset:39936
	global_load_lds_dwordx4 v130, s[62:63]
	s_mov_b32 m0, s67
	s_nop 0
	global_load_lds_dwordx4 v134, s[62:63]
	s_waitcnt vmcnt(8)
	s_waitcnt lgkmcnt(0)
	s_setprio 1
	s_barrier
	v_mfma_f32_16x16x32_bf16 v[126:129], v[148:151], v[188:191], v[126:129]
	v_mfma_f32_16x16x32_bf16 v[122:125], v[164:167], v[188:191], v[122:125]
	v_mfma_f32_16x16x32_bf16 v[110:113], v[148:151], v[198:201], v[110:113]
	v_mfma_f32_16x16x32_bf16 v[106:109], v[164:167], v[198:201], v[106:109]
	v_mfma_f32_16x16x32_bf16 v[94:97], v[148:151], v[206:209], v[94:97]
	v_mfma_f32_16x16x32_bf16 v[90:93], v[164:167], v[206:209], v[90:93]
	v_mfma_f32_16x16x32_bf16 v[78:81], v[148:151], v[214:217], v[78:81]
	v_mfma_f32_16x16x32_bf16 v[74:77], v[164:167], v[214:217], v[74:77]
	v_mfma_f32_16x16x32_bf16 v[126:129], v[152:155], v[192:195], v[126:129]
	v_mfma_f32_16x16x32_bf16 v[122:125], v[168:171], v[192:195], v[122:125]
	v_mfma_f32_16x16x32_bf16 v[110:113], v[152:155], v[202:205], v[110:113]
	v_mfma_f32_16x16x32_bf16 v[106:109], v[168:171], v[202:205], v[106:109]
	v_mfma_f32_16x16x32_bf16 v[94:97], v[152:155], v[210:213], v[94:97]
	v_mfma_f32_16x16x32_bf16 v[90:93], v[168:171], v[210:213], v[90:93]
	v_mfma_f32_16x16x32_bf16 v[78:81], v[152:155], v[218:221], v[78:81]
	v_mfma_f32_16x16x32_bf16 v[74:77], v[168:171], v[218:221], v[74:77]
	v_mfma_f32_16x16x32_bf16 v[118:121], v[172:175], v[188:191], v[118:121]
	v_mfma_f32_16x16x32_bf16 v[114:117], v[180:183], v[188:191], v[114:117]
	v_mfma_f32_16x16x32_bf16 v[102:105], v[172:175], v[198:201], v[102:105]
	v_mfma_f32_16x16x32_bf16 v[98:101], v[180:183], v[198:201], v[98:101]
	v_mfma_f32_16x16x32_bf16 v[86:89], v[172:175], v[206:209], v[86:89]
	v_mfma_f32_16x16x32_bf16 v[82:85], v[180:183], v[206:209], v[82:85]
	v_mfma_f32_16x16x32_bf16 v[70:73], v[172:175], v[214:217], v[70:73]
	v_mfma_f32_16x16x32_bf16 v[66:69], v[180:183], v[214:217], v[66:69]
	v_mfma_f32_16x16x32_bf16 v[118:121], v[176:179], v[192:195], v[118:121]
	v_mfma_f32_16x16x32_bf16 v[114:117], v[184:187], v[192:195], v[114:117]
	v_mfma_f32_16x16x32_bf16 v[102:105], v[176:179], v[202:205], v[102:105]
	v_mfma_f32_16x16x32_bf16 v[98:101], v[184:187], v[202:205], v[98:101]
	v_mfma_f32_16x16x32_bf16 v[86:89], v[176:179], v[210:213], v[86:89]
	v_mfma_f32_16x16x32_bf16 v[82:85], v[184:187], v[210:213], v[82:85]
	v_mfma_f32_16x16x32_bf16 v[70:73], v[176:179], v[218:221], v[70:73]
	v_mfma_f32_16x16x32_bf16 v[66:69], v[184:187], v[218:221], v[66:69]
	s_barrier
	s_setprio 0
	s_add_u32 s60, s60, 0x80
	s_addc_u32 s61, s61, 0
	s_add_i32 m0, s33, 0x18000
	ds_read_b128 v[188:191], v161 offset:49152
	ds_read_b128 v[192:195], v161 offset:50176
	ds_read_b128 v[198:201], v161 offset:51200
	ds_read_b128 v[202:205], v161 offset:52224
	ds_read_b128 v[206:209], v161 offset:53248
	ds_read_b128 v[210:213], v161 offset:54272
	ds_read_b128 v[214:217], v161 offset:55296
	ds_read_b128 v[218:221], v161 offset:56320
	global_load_lds_dwordx4 v132, s[60:61]
	s_add_i32 m0, s33, 0x1a000
	s_add_u32 s62, s62, 0xfff00080
	global_load_lds_dwordx4 v136, s[60:61]
	s_addc_u32 s63, s63, -1
	s_add_u32 s60, s60, 0x100000
	s_addc_u32 s61, s61, 0
	s_add_i32 m0, s33, 0x1c000
	s_nop 0
	global_load_lds_dwordx4 v132, s[60:61]
	s_add_i32 m0, s33, 0x1e000
	s_nop 0
	global_load_lds_dwordx4 v136, s[60:61]
	s_mov_b32 m0, s69
	s_nop 0
	global_load_lds_dwordx4 v130, s[62:63]
	s_mov_b32 m0, s70
	s_nop 0
	global_load_lds_dwordx4 v134, s[62:63]
	s_waitcnt vmcnt(8)
	s_waitcnt lgkmcnt(0)
	s_setprio 1
	s_barrier
	v_mfma_f32_16x16x32_bf16 v[62:65], v[148:151], v[188:191], v[62:65]
	v_mfma_f32_16x16x32_bf16 v[58:61], v[164:167], v[188:191], v[58:61]
	v_mfma_f32_16x16x32_bf16 v[46:49], v[148:151], v[198:201], v[46:49]
	v_mfma_f32_16x16x32_bf16 v[42:45], v[164:167], v[198:201], v[42:45]
	v_mfma_f32_16x16x32_bf16 v[30:33], v[148:151], v[206:209], v[30:33]
	v_mfma_f32_16x16x32_bf16 v[26:29], v[164:167], v[206:209], v[26:29]
	v_mfma_f32_16x16x32_bf16 v[14:17], v[148:151], v[214:217], v[14:17]
	v_mfma_f32_16x16x32_bf16 v[10:13], v[164:167], v[214:217], v[10:13]
	v_mfma_f32_16x16x32_bf16 v[62:65], v[152:155], v[192:195], v[62:65]
	v_mfma_f32_16x16x32_bf16 v[58:61], v[168:171], v[192:195], v[58:61]
	v_mfma_f32_16x16x32_bf16 v[46:49], v[152:155], v[202:205], v[46:49]
	v_mfma_f32_16x16x32_bf16 v[42:45], v[168:171], v[202:205], v[42:45]
	v_mfma_f32_16x16x32_bf16 v[30:33], v[152:155], v[210:213], v[30:33]
	v_mfma_f32_16x16x32_bf16 v[26:29], v[168:171], v[210:213], v[26:29]
	v_mfma_f32_16x16x32_bf16 v[14:17], v[152:155], v[218:221], v[14:17]
	v_mfma_f32_16x16x32_bf16 v[10:13], v[168:171], v[218:221], v[10:13]
	v_mfma_f32_16x16x32_bf16 v[54:57], v[172:175], v[188:191], v[54:57]
	v_mfma_f32_16x16x32_bf16 v[50:53], v[180:183], v[188:191], v[50:53]
	v_mfma_f32_16x16x32_bf16 v[38:41], v[172:175], v[198:201], v[38:41]
	v_mfma_f32_16x16x32_bf16 v[34:37], v[180:183], v[198:201], v[34:37]
	v_mfma_f32_16x16x32_bf16 v[22:25], v[172:175], v[206:209], v[22:25]
	v_mfma_f32_16x16x32_bf16 v[18:21], v[180:183], v[206:209], v[18:21]
	v_mfma_f32_16x16x32_bf16 v[6:9], v[172:175], v[214:217], v[6:9]
	v_mfma_f32_16x16x32_bf16 v[2:5], v[180:183], v[214:217], v[2:5]
	v_mfma_f32_16x16x32_bf16 v[54:57], v[176:179], v[192:195], v[54:57]
	v_mfma_f32_16x16x32_bf16 v[50:53], v[184:187], v[192:195], v[50:53]
	v_mfma_f32_16x16x32_bf16 v[38:41], v[176:179], v[202:205], v[38:41]
	v_mfma_f32_16x16x32_bf16 v[34:37], v[184:187], v[202:205], v[34:37]
	v_mfma_f32_16x16x32_bf16 v[22:25], v[176:179], v[210:213], v[22:25]
	v_mfma_f32_16x16x32_bf16 v[18:21], v[184:187], v[210:213], v[18:21]
	v_mfma_f32_16x16x32_bf16 v[6:9], v[176:179], v[218:221], v[6:9]
	v_mfma_f32_16x16x32_bf16 v[2:5], v[184:187], v[218:221], v[2:5]
	s_barrier
	s_setprio 0
	s_add_i32 s78, s78, 2
	s_add_u32 s58, s58, 0x100
	s_addc_u32 s59, s59, 0
	s_add_u32 s76, s76, 0x100
	s_addc_u32 s77, s77, 0
	s_cmp_gt_u32 s78, 61

.LBB0_806:
	s_ashr_i32 s35, s34, 31
	s_lshl_b64 s[36:37], s[34:35], 21
	s_add_u32 s36, s8, s36
	s_addc_u32 s37, s9, s37
	s_and_b64 s[38:39], s[0:1], exec
	s_cselect_b32 s35, s37, s43
	s_cselect_b32 s64, s36, s42
	s_ashr_i32 s31, s30, 31
	s_lshl_b64 s[38:39], s[30:31], 21
	s_add_u32 s38, s76, s38
	s_addc_u32 s39, s77, s39
	s_and_b64 s[46:47], s[0:1], exec
	s_cselect_b32 s31, s39, s45
	s_cselect_b32 s65, s38, s44
	s_add_u32 s42, s42, 0x100080
	s_addc_u32 s43, s43, 0
	s_add_u32 s66, s44, 0x100
	s_addc_u32 s67, s45, 0
	s_mov_b32 s68, -2
	ds_read_b128 v[154:157], v150
	ds_read_b128 v[158:161], v150 offset:1024
	ds_read_b128 v[162:165], v150 offset:2048
	ds_read_b128 v[166:169], v150 offset:3072
	ds_read_b128 v[170:173], v151
	ds_read_b128 v[174:177], v151 offset:1024
	ds_read_b128 v[178:181], v151 offset:2048
	ds_read_b128 v[182:185], v151 offset:3072
	s_add_u32 s44, s42, 0xfff00080
	s_addc_u32 s45, s43, -1
	s_cmp_eq_u32 s68, 60
	s_cselect_b32 s47, s35, s45
	s_cselect_b32 s46, s64, s44
	s_cselect_b32 s45, s31, s67
	s_cselect_b32 s44, s65, s66
	s_add_i32 m0, s41, 0xc000
	ds_read_b128 v[186:189], v152
	ds_read_b128 v[190:193], v152 offset:1024
	ds_read_b128 v[198:201], v152 offset:2048
	ds_read_b128 v[202:205], v152 offset:3072
	ds_read_b128 v[206:209], v152 offset:4096
	ds_read_b128 v[210:213], v152 offset:5120
	ds_read_b128 v[214:217], v152 offset:6144
	ds_read_b128 v[218:221], v152 offset:7168
	global_load_lds_dwordx4 v138, s[42:43]
	s_add_i32 m0, s41, 0xe000
	s_nop 0
	global_load_lds_dwordx4 v140, s[42:43]
	s_waitcnt vmcnt(8)
	s_waitcnt lgkmcnt(0)
	s_setprio 1
	s_barrier
	v_mfma_f32_16x16x32_bf16 v[126:129], v[154:157], v[186:189], 0
	v_mfma_f32_16x16x32_bf16 v[122:125], v[162:165], v[186:189], 0
	v_mfma_f32_16x16x32_bf16 v[110:113], v[154:157], v[198:201], 0
	v_mfma_f32_16x16x32_bf16 v[106:109], v[162:165], v[198:201], 0
	v_mfma_f32_16x16x32_bf16 v[94:97], v[154:157], v[206:209], 0
	v_mfma_f32_16x16x32_bf16 v[90:93], v[162:165], v[206:209], 0
	v_mfma_f32_16x16x32_bf16 v[78:81], v[154:157], v[214:217], 0
	v_mfma_f32_16x16x32_bf16 v[74:77], v[162:165], v[214:217], 0
	v_mfma_f32_16x16x32_bf16 v[126:129], v[158:161], v[190:193], v[126:129]
	v_mfma_f32_16x16x32_bf16 v[122:125], v[166:169], v[190:193], v[122:125]
	v_mfma_f32_16x16x32_bf16 v[110:113], v[158:161], v[202:205], v[110:113]
	v_mfma_f32_16x16x32_bf16 v[106:109], v[166:169], v[202:205], v[106:109]
	v_mfma_f32_16x16x32_bf16 v[94:97], v[158:161], v[210:213], v[94:97]
	v_mfma_f32_16x16x32_bf16 v[90:93], v[166:169], v[210:213], v[90:93]
	v_mfma_f32_16x16x32_bf16 v[78:81], v[158:161], v[218:221], v[78:81]
	v_mfma_f32_16x16x32_bf16 v[74:77], v[166:169], v[218:221], v[74:77]
	v_mfma_f32_16x16x32_bf16 v[118:121], v[170:173], v[186:189], 0
	v_mfma_f32_16x16x32_bf16 v[114:117], v[178:181], v[186:189], 0
	v_mfma_f32_16x16x32_bf16 v[102:105], v[170:173], v[198:201], 0
	v_mfma_f32_16x16x32_bf16 v[98:101], v[178:181], v[198:201], 0
	v_mfma_f32_16x16x32_bf16 v[86:89], v[170:173], v[206:209], 0
	v_mfma_f32_16x16x32_bf16 v[82:85], v[178:181], v[206:209], 0
	v_mfma_f32_16x16x32_bf16 v[70:73], v[170:173], v[214:217], 0
	v_mfma_f32_16x16x32_bf16 v[66:69], v[178:181], v[214:217], 0
	v_mfma_f32_16x16x32_bf16 v[118:121], v[174:177], v[190:193], v[118:121]
	v_mfma_f32_16x16x32_bf16 v[114:117], v[182:185], v[190:193], v[114:117]
	v_mfma_f32_16x16x32_bf16 v[102:105], v[174:177], v[202:205], v[102:105]
	v_mfma_f32_16x16x32_bf16 v[98:101], v[182:185], v[202:205], v[98:101]
	v_mfma_f32_16x16x32_bf16 v[86:89], v[174:177], v[210:213], v[86:89]
	v_mfma_f32_16x16x32_bf16 v[82:85], v[182:185], v[210:213], v[82:85]
	v_mfma_f32_16x16x32_bf16 v[70:73], v[174:177], v[218:221], v[70:73]
	v_mfma_f32_16x16x32_bf16 v[66:69], v[182:185], v[218:221], v[66:69]
	s_barrier
	s_setprio 0
	s_add_i32 s69, s57, s33
	s_mov_b32 m0, s69
	ds_read_b128 v[186:189], v152 offset:16384
	ds_read_b128 v[190:193], v152 offset:17408
	ds_read_b128 v[198:201], v152 offset:18432
	ds_read_b128 v[202:205], v152 offset:19456
	ds_read_b128 v[206:209], v152 offset:20480
	ds_read_b128 v[210:213], v152 offset:21504
	ds_read_b128 v[214:217], v152 offset:22528
	ds_read_b128 v[218:221], v152 offset:23552
	global_load_lds_dwordx4 v132, s[44:45]
	s_add_i32 m0, s69, 0x2000
	s_add_u32 s70, s44, 0x100000
	s_addc_u32 s71, s45, 0
	s_add_i32 s69, s58, s33
	global_load_lds_dwordx4 v136, s[44:45]
	s_mov_b32 m0, s69
	global_load_lds_dwordx4 v132, s[70:71]
	s_add_i32 m0, s69, 0x2000
	s_nop 0
	global_load_lds_dwordx4 v136, s[70:71]
	s_mov_b32 m0, s41
	s_nop 0
	global_load_lds_dwordx4 v130, s[46:47]
	s_mov_b32 m0, s50
	s_nop 0
	global_load_lds_dwordx4 v134, s[46:47]
	s_waitcnt vmcnt(8)
	s_waitcnt lgkmcnt(0)
	s_setprio 1
	s_barrier
	v_mfma_f32_16x16x32_bf16 v[62:65], v[154:157], v[186:189], 0
	v_mfma_f32_16x16x32_bf16 v[58:61], v[162:165], v[186:189], 0
	v_mfma_f32_16x16x32_bf16 v[46:49], v[154:157], v[198:201], 0
	v_mfma_f32_16x16x32_bf16 v[42:45], v[162:165], v[198:201], 0
	v_mfma_f32_16x16x32_bf16 v[30:33], v[154:157], v[206:209], 0
	v_mfma_f32_16x16x32_bf16 v[26:29], v[162:165], v[206:209], 0
	v_mfma_f32_16x16x32_bf16 v[14:17], v[154:157], v[214:217], 0
	v_mfma_f32_16x16x32_bf16 v[10:13], v[162:165], v[214:217], 0
	v_mfma_f32_16x16x32_bf16 v[62:65], v[158:161], v[190:193], v[62:65]
	v_mfma_f32_16x16x32_bf16 v[58:61], v[166:169], v[190:193], v[58:61]
	v_mfma_f32_16x16x32_bf16 v[46:49], v[158:161], v[202:205], v[46:49]
	v_mfma_f32_16x16x32_bf16 v[42:45], v[166:169], v[202:205], v[42:45]
	v_mfma_f32_16x16x32_bf16 v[30:33], v[158:161], v[210:213], v[30:33]
	v_mfma_f32_16x16x32_bf16 v[26:29], v[166:169], v[210:213], v[26:29]
	v_mfma_f32_16x16x32_bf16 v[14:17], v[158:161], v[218:221], v[14:17]
	v_mfma_f32_16x16x32_bf16 v[10:13], v[166:169], v[218:221], v[10:13]
	v_mfma_f32_16x16x32_bf16 v[54:57], v[170:173], v[186:189], 0
	v_mfma_f32_16x16x32_bf16 v[50:53], v[178:181], v[186:189], 0
	v_mfma_f32_16x16x32_bf16 v[38:41], v[170:173], v[198:201], 0
	v_mfma_f32_16x16x32_bf16 v[34:37], v[178:181], v[198:201], 0
	v_mfma_f32_16x16x32_bf16 v[22:25], v[170:173], v[206:209], 0
	v_mfma_f32_16x16x32_bf16 v[18:21], v[178:181], v[206:209], 0
	v_mfma_f32_16x16x32_bf16 v[6:9], v[170:173], v[214:217], 0
	v_mfma_f32_16x16x32_bf16 v[2:5], v[178:181], v[214:217], 0
	v_mfma_f32_16x16x32_bf16 v[54:57], v[174:177], v[190:193], v[54:57]
	v_mfma_f32_16x16x32_bf16 v[50:53], v[182:185], v[190:193], v[50:53]
	v_mfma_f32_16x16x32_bf16 v[38:41], v[174:177], v[202:205], v[38:41]
	v_mfma_f32_16x16x32_bf16 v[34:37], v[182:185], v[202:205], v[34:37]
	v_mfma_f32_16x16x32_bf16 v[22:25], v[174:177], v[210:213], v[22:25]
	v_mfma_f32_16x16x32_bf16 v[18:21], v[182:185], v[210:213], v[18:21]
	v_mfma_f32_16x16x32_bf16 v[6:9], v[174:177], v[218:221], v[6:9]
	v_mfma_f32_16x16x32_bf16 v[2:5], v[182:185], v[218:221], v[2:5]
	s_barrier
	s_setprio 0
	s_add_i32 s69, 0, 0x18000
	v_add_u32_e32 v153, s69, v148
	s_add_i32 s70, 0, 0x1c000
	ds_read_b128 v[154:157], v153
	ds_read_b128 v[158:161], v153 offset:1024
	ds_read_b128 v[162:165], v153 offset:2048
	ds_read_b128 v[166:169], v153 offset:3072
	v_add_u32_e32 v153, s70, v148
	ds_read_b128 v[170:173], v153
	ds_read_b128 v[174:177], v153 offset:1024
	ds_read_b128 v[178:181], v153 offset:2048
	ds_read_b128 v[182:185], v153 offset:3072
	s_add_u32 s46, s46, 0x100000
	s_addc_u32 s47, s47, 0
	s_mov_b32 m0, s51
	ds_read_b128 v[186:189], v152 offset:32768
	ds_read_b128 v[190:193], v152 offset:33792
	ds_read_b128 v[198:201], v152 offset:34816
	ds_read_b128 v[202:205], v152 offset:35840
	ds_read_b128 v[206:209], v152 offset:36864
	ds_read_b128 v[210:213], v152 offset:37888
	ds_read_b128 v[214:217], v152 offset:38912
	ds_read_b128 v[218:221], v152 offset:39936
	global_load_lds_dwordx4 v130, s[46:47]
	s_mov_b32 m0, s52
	s_nop 0
	global_load_lds_dwordx4 v134, s[46:47]
	s_waitcnt vmcnt(8)
	s_waitcnt lgkmcnt(0)
	s_setprio 1
	s_barrier
	v_mfma_f32_16x16x32_bf16 v[126:129], v[154:157], v[186:189], v[126:129]
	v_mfma_f32_16x16x32_bf16 v[122:125], v[162:165], v[186:189], v[122:125]
	v_mfma_f32_16x16x32_bf16 v[110:113], v[154:157], v[198:201], v[110:113]
	v_mfma_f32_16x16x32_bf16 v[106:109], v[162:165], v[198:201], v[106:109]
	v_mfma_f32_16x16x32_bf16 v[94:97], v[154:157], v[206:209], v[94:97]
	v_mfma_f32_16x16x32_bf16 v[90:93], v[162:165], v[206:209], v[90:93]
	v_mfma_f32_16x16x32_bf16 v[78:81], v[154:157], v[214:217], v[78:81]
	v_mfma_f32_16x16x32_bf16 v[74:77], v[162:165], v[214:217], v[74:77]
	v_mfma_f32_16x16x32_bf16 v[126:129], v[158:161], v[190:193], v[126:129]
	v_mfma_f32_16x16x32_bf16 v[122:125], v[166:169], v[190:193], v[122:125]
	v_mfma_f32_16x16x32_bf16 v[110:113], v[158:161], v[202:205], v[110:113]
	v_mfma_f32_16x16x32_bf16 v[106:109], v[166:169], v[202:205], v[106:109]
	v_mfma_f32_16x16x32_bf16 v[94:97], v[158:161], v[210:213], v[94:97]
	v_mfma_f32_16x16x32_bf16 v[90:93], v[166:169], v[210:213], v[90:93]
	v_mfma_f32_16x16x32_bf16 v[78:81], v[158:161], v[218:221], v[78:81]
	v_mfma_f32_16x16x32_bf16 v[74:77], v[166:169], v[218:221], v[74:77]
	v_mfma_f32_16x16x32_bf16 v[118:121], v[170:173], v[186:189], v[118:121]
	v_mfma_f32_16x16x32_bf16 v[114:117], v[178:181], v[186:189], v[114:117]
	v_mfma_f32_16x16x32_bf16 v[102:105], v[170:173], v[198:201], v[102:105]
	v_mfma_f32_16x16x32_bf16 v[98:101], v[178:181], v[198:201], v[98:101]
	v_mfma_f32_16x16x32_bf16 v[86:89], v[170:173], v[206:209], v[86:89]
	v_mfma_f32_16x16x32_bf16 v[82:85], v[178:181], v[206:209], v[82:85]
	v_mfma_f32_16x16x32_bf16 v[70:73], v[170:173], v[214:217], v[70:73]
	v_mfma_f32_16x16x32_bf16 v[66:69], v[178:181], v[214:217], v[66:69]
	v_mfma_f32_16x16x32_bf16 v[118:121], v[174:177], v[190:193], v[118:121]
	v_mfma_f32_16x16x32_bf16 v[114:117], v[182:185], v[190:193], v[114:117]
	v_mfma_f32_16x16x32_bf16 v[102:105], v[174:177], v[202:205], v[102:105]
	v_mfma_f32_16x16x32_bf16 v[98:101], v[182:185], v[202:205], v[98:101]
	v_mfma_f32_16x16x32_bf16 v[86:89], v[174:177], v[210:213], v[86:89]
	v_mfma_f32_16x16x32_bf16 v[82:85], v[182:185], v[210:213], v[82:85]
	v_mfma_f32_16x16x32_bf16 v[70:73], v[174:177], v[218:221], v[70:73]
	v_mfma_f32_16x16x32_bf16 v[66:69], v[182:185], v[218:221], v[66:69]
	s_barrier
	s_setprio 0
	s_add_u32 s44, s44, 0x80
	s_addc_u32 s45, s45, 0
	s_add_i32 m0, s33, 0x18000
	ds_read_b128 v[186:189], v152 offset:49152
	ds_read_b128 v[190:193], v152 offset:50176
	ds_read_b128 v[198:201], v152 offset:51200
	ds_read_b128 v[202:205], v152 offset:52224
	ds_read_b128 v[206:209], v152 offset:53248
	ds_read_b128 v[210:213], v152 offset:54272
	ds_read_b128 v[214:217], v152 offset:55296
	ds_read_b128 v[218:221], v152 offset:56320
	global_load_lds_dwordx4 v132, s[44:45]
	s_add_i32 m0, s33, 0x1a000
	s_add_u32 s46, s46, 0xfff00080
	global_load_lds_dwordx4 v136, s[44:45]
	s_addc_u32 s47, s47, -1
	s_add_u32 s44, s44, 0x100000
	s_addc_u32 s45, s45, 0
	s_add_i32 m0, s33, 0x1c000
	s_nop 0
	global_load_lds_dwordx4 v132, s[44:45]
	s_add_i32 m0, s33, 0x1e000
	s_nop 0
	global_load_lds_dwordx4 v136, s[44:45]
	s_mov_b32 m0, s55
	s_nop 0
	global_load_lds_dwordx4 v130, s[46:47]
	s_mov_b32 m0, s56
	s_nop 0
	global_load_lds_dwordx4 v134, s[46:47]
	s_waitcnt vmcnt(8)
	s_waitcnt lgkmcnt(0)
	s_setprio 1
	s_barrier
	v_mfma_f32_16x16x32_bf16 v[62:65], v[154:157], v[186:189], v[62:65]
	v_mfma_f32_16x16x32_bf16 v[58:61], v[162:165], v[186:189], v[58:61]
	v_mfma_f32_16x16x32_bf16 v[46:49], v[154:157], v[198:201], v[46:49]
	v_mfma_f32_16x16x32_bf16 v[42:45], v[162:165], v[198:201], v[42:45]
	v_mfma_f32_16x16x32_bf16 v[30:33], v[154:157], v[206:209], v[30:33]
	v_mfma_f32_16x16x32_bf16 v[26:29], v[162:165], v[206:209], v[26:29]
	v_mfma_f32_16x16x32_bf16 v[14:17], v[154:157], v[214:217], v[14:17]
	v_mfma_f32_16x16x32_bf16 v[10:13], v[162:165], v[214:217], v[10:13]
	v_mfma_f32_16x16x32_bf16 v[62:65], v[158:161], v[190:193], v[62:65]
	v_mfma_f32_16x16x32_bf16 v[58:61], v[166:169], v[190:193], v[58:61]
	v_mfma_f32_16x16x32_bf16 v[46:49], v[158:161], v[202:205], v[46:49]
	v_mfma_f32_16x16x32_bf16 v[42:45], v[166:169], v[202:205], v[42:45]
	v_mfma_f32_16x16x32_bf16 v[30:33], v[158:161], v[210:213], v[30:33]
	v_mfma_f32_16x16x32_bf16 v[26:29], v[166:169], v[210:213], v[26:29]
	v_mfma_f32_16x16x32_bf16 v[14:17], v[158:161], v[218:221], v[14:17]
	v_mfma_f32_16x16x32_bf16 v[10:13], v[166:169], v[218:221], v[10:13]
	v_mfma_f32_16x16x32_bf16 v[54:57], v[170:173], v[186:189], v[54:57]
	v_mfma_f32_16x16x32_bf16 v[50:53], v[178:181], v[186:189], v[50:53]
	v_mfma_f32_16x16x32_bf16 v[38:41], v[170:173], v[198:201], v[38:41]
	v_mfma_f32_16x16x32_bf16 v[34:37], v[178:181], v[198:201], v[34:37]
	v_mfma_f32_16x16x32_bf16 v[22:25], v[170:173], v[206:209], v[22:25]
	v_mfma_f32_16x16x32_bf16 v[18:21], v[178:181], v[206:209], v[18:21]
	v_mfma_f32_16x16x32_bf16 v[6:9], v[170:173], v[214:217], v[6:9]
	v_mfma_f32_16x16x32_bf16 v[2:5], v[178:181], v[214:217], v[2:5]
	v_mfma_f32_16x16x32_bf16 v[54:57], v[174:177], v[190:193], v[54:57]
	v_mfma_f32_16x16x32_bf16 v[50:53], v[182:185], v[190:193], v[50:53]
	v_mfma_f32_16x16x32_bf16 v[38:41], v[174:177], v[202:205], v[38:41]
	v_mfma_f32_16x16x32_bf16 v[34:37], v[182:185], v[202:205], v[34:37]
	v_mfma_f32_16x16x32_bf16 v[22:25], v[174:177], v[210:213], v[22:25]
	v_mfma_f32_16x16x32_bf16 v[18:21], v[182:185], v[210:213], v[18:21]
	v_mfma_f32_16x16x32_bf16 v[6:9], v[174:177], v[218:221], v[6:9]
	v_mfma_f32_16x16x32_bf16 v[2:5], v[182:185], v[218:221], v[2:5]
	s_barrier
	s_setprio 0
	s_add_i32 s68, s68, 2
	s_add_u32 s42, s42, 0x100
	s_addc_u32 s43, s43, 0
	s_add_u32 s66, s66, 0x100
	s_addc_u32 s67, s67, 0
	s_cmp_gt_u32 s68, 61

.LBB0_896:
	s_ashr_i32 s35, s34, 31
	s_lshl_b64 s[36:37], s[34:35], 23
	s_add_u32 s36, s86, s36
	s_addc_u32 s37, s87, s37
	s_and_b64 s[38:39], s[0:1], exec
	s_cselect_b32 s35, s37, s43
	s_cselect_b32 s63, s36, s42
	s_ashr_i32 s31, s30, 31
	s_lshl_b64 s[38:39], s[30:31], 23
	s_add_u32 s38, s10, s38
	s_addc_u32 s39, s11, s39
	s_and_b64 s[46:47], s[0:1], exec
	s_cselect_b32 s31, s39, s45
	s_cselect_b32 s64, s38, s44
	s_add_u32 s42, s42, 0x400080
	s_addc_u32 s43, s43, 0
	s_add_u32 s65, s44, 0x100
	s_addc_u32 s66, s45, 0
	s_mov_b32 s67, -2
	ds_read_b128 v[146:149], v156
	ds_read_b128 v[150:153], v156 offset:1024
	ds_read_b128 v[160:163], v156 offset:2048
	ds_read_b128 v[164:167], v156 offset:3072
	ds_read_b128 v[168:171], v157
	ds_read_b128 v[172:175], v157 offset:1024
	ds_read_b128 v[176:179], v157 offset:2048
	ds_read_b128 v[180:183], v157 offset:3072
	s_add_u32 s44, s42, 0xffc00080
	s_addc_u32 s45, s43, -1
	s_cmpk_eq_i32 s67, 0xfc
	s_cselect_b32 s47, s35, s45
	s_cselect_b32 s46, s63, s44
	s_cselect_b32 s45, s31, s66
	s_cselect_b32 s44, s64, s65
	s_add_i32 m0, s41, 0xc000
	ds_read_b128 v[184:187], v158
	ds_read_b128 v[188:191], v158 offset:1024
	ds_read_b128 v[192:195], v158 offset:2048
	ds_read_b128 v[198:201], v158 offset:3072
	ds_read_b128 v[202:205], v158 offset:4096
	ds_read_b128 v[206:209], v158 offset:5120
	ds_read_b128 v[210:213], v158 offset:6144
	ds_read_b128 v[214:217], v158 offset:7168
	global_load_lds_dwordx4 v138, s[42:43]
	s_add_i32 m0, s41, 0xe000
	s_nop 0
	global_load_lds_dwordx4 v140, s[42:43]
	s_waitcnt vmcnt(8)
	s_waitcnt lgkmcnt(0)
	s_setprio 1
	s_barrier
	v_mfma_f32_16x16x32_bf16 v[126:129], v[146:149], v[184:187], 0
	v_mfma_f32_16x16x32_bf16 v[122:125], v[160:163], v[184:187], 0
	v_mfma_f32_16x16x32_bf16 v[110:113], v[146:149], v[192:195], 0
	v_mfma_f32_16x16x32_bf16 v[106:109], v[160:163], v[192:195], 0
	v_mfma_f32_16x16x32_bf16 v[94:97], v[146:149], v[202:205], 0
	v_mfma_f32_16x16x32_bf16 v[90:93], v[160:163], v[202:205], 0
	v_mfma_f32_16x16x32_bf16 v[78:81], v[146:149], v[210:213], 0
	v_mfma_f32_16x16x32_bf16 v[74:77], v[160:163], v[210:213], 0
	v_mfma_f32_16x16x32_bf16 v[126:129], v[150:153], v[188:191], v[126:129]
	v_mfma_f32_16x16x32_bf16 v[122:125], v[164:167], v[188:191], v[122:125]
	v_mfma_f32_16x16x32_bf16 v[110:113], v[150:153], v[198:201], v[110:113]
	v_mfma_f32_16x16x32_bf16 v[106:109], v[164:167], v[198:201], v[106:109]
	v_mfma_f32_16x16x32_bf16 v[94:97], v[150:153], v[206:209], v[94:97]
	v_mfma_f32_16x16x32_bf16 v[90:93], v[164:167], v[206:209], v[90:93]
	v_mfma_f32_16x16x32_bf16 v[78:81], v[150:153], v[214:217], v[78:81]
	v_mfma_f32_16x16x32_bf16 v[74:77], v[164:167], v[214:217], v[74:77]
	v_mfma_f32_16x16x32_bf16 v[118:121], v[168:171], v[184:187], 0
	v_mfma_f32_16x16x32_bf16 v[114:117], v[176:179], v[184:187], 0
	v_mfma_f32_16x16x32_bf16 v[102:105], v[168:171], v[192:195], 0
	v_mfma_f32_16x16x32_bf16 v[98:101], v[176:179], v[192:195], 0
	v_mfma_f32_16x16x32_bf16 v[86:89], v[168:171], v[202:205], 0
	v_mfma_f32_16x16x32_bf16 v[82:85], v[176:179], v[202:205], 0
	v_mfma_f32_16x16x32_bf16 v[70:73], v[168:171], v[210:213], 0
	v_mfma_f32_16x16x32_bf16 v[66:69], v[176:179], v[210:213], 0
	v_mfma_f32_16x16x32_bf16 v[118:121], v[172:175], v[188:191], v[118:121]
	v_mfma_f32_16x16x32_bf16 v[114:117], v[180:183], v[188:191], v[114:117]
	v_mfma_f32_16x16x32_bf16 v[102:105], v[172:175], v[198:201], v[102:105]
	v_mfma_f32_16x16x32_bf16 v[98:101], v[180:183], v[198:201], v[98:101]
	v_mfma_f32_16x16x32_bf16 v[86:89], v[172:175], v[206:209], v[86:89]
	v_mfma_f32_16x16x32_bf16 v[82:85], v[180:183], v[206:209], v[82:85]
	v_mfma_f32_16x16x32_bf16 v[70:73], v[172:175], v[214:217], v[70:73]
	v_mfma_f32_16x16x32_bf16 v[66:69], v[180:183], v[214:217], v[66:69]
	s_barrier
	s_setprio 0
	s_add_i32 s68, s56, s48
	s_mov_b32 m0, s68
	ds_read_b128 v[184:187], v158 offset:16384
	ds_read_b128 v[188:191], v158 offset:17408
	ds_read_b128 v[192:195], v158 offset:18432
	ds_read_b128 v[198:201], v158 offset:19456
	ds_read_b128 v[202:205], v158 offset:20480
	ds_read_b128 v[206:209], v158 offset:21504
	ds_read_b128 v[210:213], v158 offset:22528
	ds_read_b128 v[214:217], v158 offset:23552
	global_load_lds_dwordx4 v132, s[44:45]
	s_add_i32 m0, s68, 0x2000
	s_add_u32 s68, s44, 0x400000
	s_addc_u32 s69, s45, 0
	s_add_i32 s70, s57, s48
	global_load_lds_dwordx4 v136, s[44:45]
	s_mov_b32 m0, s70
	global_load_lds_dwordx4 v132, s[68:69]
	s_add_i32 m0, s70, 0x2000
	s_nop 0
	global_load_lds_dwordx4 v136, s[68:69]
	s_mov_b32 m0, s41
	s_nop 0
	global_load_lds_dwordx4 v130, s[46:47]
	s_mov_b32 m0, s49
	s_nop 0
	global_load_lds_dwordx4 v134, s[46:47]
	s_waitcnt vmcnt(8)
	s_waitcnt lgkmcnt(0)
	s_setprio 1
	s_barrier
	v_mfma_f32_16x16x32_bf16 v[62:65], v[146:149], v[184:187], 0
	v_mfma_f32_16x16x32_bf16 v[58:61], v[160:163], v[184:187], 0
	v_mfma_f32_16x16x32_bf16 v[46:49], v[146:149], v[192:195], 0
	v_mfma_f32_16x16x32_bf16 v[42:45], v[160:163], v[192:195], 0
	v_mfma_f32_16x16x32_bf16 v[30:33], v[146:149], v[202:205], 0
	v_mfma_f32_16x16x32_bf16 v[26:29], v[160:163], v[202:205], 0
	v_mfma_f32_16x16x32_bf16 v[14:17], v[146:149], v[210:213], 0
	v_mfma_f32_16x16x32_bf16 v[10:13], v[160:163], v[210:213], 0
	v_mfma_f32_16x16x32_bf16 v[62:65], v[150:153], v[188:191], v[62:65]
	v_mfma_f32_16x16x32_bf16 v[58:61], v[164:167], v[188:191], v[58:61]
	v_mfma_f32_16x16x32_bf16 v[46:49], v[150:153], v[198:201], v[46:49]
	v_mfma_f32_16x16x32_bf16 v[42:45], v[164:167], v[198:201], v[42:45]
	v_mfma_f32_16x16x32_bf16 v[30:33], v[150:153], v[206:209], v[30:33]
	v_mfma_f32_16x16x32_bf16 v[26:29], v[164:167], v[206:209], v[26:29]
	v_mfma_f32_16x16x32_bf16 v[14:17], v[150:153], v[214:217], v[14:17]
	v_mfma_f32_16x16x32_bf16 v[10:13], v[164:167], v[214:217], v[10:13]
	v_mfma_f32_16x16x32_bf16 v[54:57], v[168:171], v[184:187], 0
	v_mfma_f32_16x16x32_bf16 v[50:53], v[176:179], v[184:187], 0
	v_mfma_f32_16x16x32_bf16 v[38:41], v[168:171], v[192:195], 0
	v_mfma_f32_16x16x32_bf16 v[34:37], v[176:179], v[192:195], 0
	v_mfma_f32_16x16x32_bf16 v[22:25], v[168:171], v[202:205], 0
	v_mfma_f32_16x16x32_bf16 v[18:21], v[176:179], v[202:205], 0
	v_mfma_f32_16x16x32_bf16 v[6:9], v[168:171], v[210:213], 0
	v_mfma_f32_16x16x32_bf16 v[2:5], v[176:179], v[210:213], 0
	v_mfma_f32_16x16x32_bf16 v[54:57], v[172:175], v[188:191], v[54:57]
	v_mfma_f32_16x16x32_bf16 v[50:53], v[180:183], v[188:191], v[50:53]
	v_mfma_f32_16x16x32_bf16 v[38:41], v[172:175], v[198:201], v[38:41]
	v_mfma_f32_16x16x32_bf16 v[34:37], v[180:183], v[198:201], v[34:37]
	v_mfma_f32_16x16x32_bf16 v[22:25], v[172:175], v[206:209], v[22:25]
	v_mfma_f32_16x16x32_bf16 v[18:21], v[180:183], v[206:209], v[18:21]
	v_mfma_f32_16x16x32_bf16 v[6:9], v[172:175], v[214:217], v[6:9]
	v_mfma_f32_16x16x32_bf16 v[2:5], v[180:183], v[214:217], v[2:5]
	s_barrier
	s_setprio 0
	s_add_i32 s68, 0, 0x18000
	s_add_i32 s69, 0, 0x1c000
	v_add_u32_e32 v164, s68, v154
	v_add_u32_e32 v180, s69, v154
	ds_read_b128 v[146:149], v164
	ds_read_b128 v[150:153], v164 offset:1024
	ds_read_b128 v[160:163], v164 offset:2048
	ds_read_b128 v[164:167], v164 offset:3072
	ds_read_b128 v[168:171], v180
	ds_read_b128 v[172:175], v180 offset:1024
	ds_read_b128 v[176:179], v180 offset:2048
	ds_read_b128 v[180:183], v180 offset:3072
	s_add_u32 s46, s46, 0x400000
	s_addc_u32 s47, s47, 0
	s_mov_b32 m0, s50
	ds_read_b128 v[184:187], v158 offset:32768
	ds_read_b128 v[188:191], v158 offset:33792
	ds_read_b128 v[192:195], v158 offset:34816
	ds_read_b128 v[198:201], v158 offset:35840
	ds_read_b128 v[202:205], v158 offset:36864
	ds_read_b128 v[206:209], v158 offset:37888
	ds_read_b128 v[210:213], v158 offset:38912
	ds_read_b128 v[214:217], v158 offset:39936
	global_load_lds_dwordx4 v130, s[46:47]
	s_mov_b32 m0, s51
	s_nop 0
	global_load_lds_dwordx4 v134, s[46:47]
	s_waitcnt vmcnt(8)
	s_waitcnt lgkmcnt(0)
	s_setprio 1
	s_barrier
	v_mfma_f32_16x16x32_bf16 v[126:129], v[146:149], v[184:187], v[126:129]
	v_mfma_f32_16x16x32_bf16 v[122:125], v[160:163], v[184:187], v[122:125]
	v_mfma_f32_16x16x32_bf16 v[110:113], v[146:149], v[192:195], v[110:113]
	v_mfma_f32_16x16x32_bf16 v[106:109], v[160:163], v[192:195], v[106:109]
	v_mfma_f32_16x16x32_bf16 v[94:97], v[146:149], v[202:205], v[94:97]
	v_mfma_f32_16x16x32_bf16 v[90:93], v[160:163], v[202:205], v[90:93]
	v_mfma_f32_16x16x32_bf16 v[78:81], v[146:149], v[210:213], v[78:81]
	v_mfma_f32_16x16x32_bf16 v[74:77], v[160:163], v[210:213], v[74:77]
	v_mfma_f32_16x16x32_bf16 v[126:129], v[150:153], v[188:191], v[126:129]
	v_mfma_f32_16x16x32_bf16 v[122:125], v[164:167], v[188:191], v[122:125]
	v_mfma_f32_16x16x32_bf16 v[110:113], v[150:153], v[198:201], v[110:113]
	v_mfma_f32_16x16x32_bf16 v[106:109], v[164:167], v[198:201], v[106:109]
	v_mfma_f32_16x16x32_bf16 v[94:97], v[150:153], v[206:209], v[94:97]
	v_mfma_f32_16x16x32_bf16 v[90:93], v[164:167], v[206:209], v[90:93]
	v_mfma_f32_16x16x32_bf16 v[78:81], v[150:153], v[214:217], v[78:81]
	v_mfma_f32_16x16x32_bf16 v[74:77], v[164:167], v[214:217], v[74:77]
	v_mfma_f32_16x16x32_bf16 v[118:121], v[168:171], v[184:187], v[118:121]
	v_mfma_f32_16x16x32_bf16 v[114:117], v[176:179], v[184:187], v[114:117]
	v_mfma_f32_16x16x32_bf16 v[102:105], v[168:171], v[192:195], v[102:105]
	v_mfma_f32_16x16x32_bf16 v[98:101], v[176:179], v[192:195], v[98:101]
	v_mfma_f32_16x16x32_bf16 v[86:89], v[168:171], v[202:205], v[86:89]
	v_mfma_f32_16x16x32_bf16 v[82:85], v[176:179], v[202:205], v[82:85]
	v_mfma_f32_16x16x32_bf16 v[70:73], v[168:171], v[210:213], v[70:73]
	v_mfma_f32_16x16x32_bf16 v[66:69], v[176:179], v[210:213], v[66:69]
	v_mfma_f32_16x16x32_bf16 v[118:121], v[172:175], v[188:191], v[118:121]
	v_mfma_f32_16x16x32_bf16 v[114:117], v[180:183], v[188:191], v[114:117]
	v_mfma_f32_16x16x32_bf16 v[102:105], v[172:175], v[198:201], v[102:105]
	v_mfma_f32_16x16x32_bf16 v[98:101], v[180:183], v[198:201], v[98:101]
	v_mfma_f32_16x16x32_bf16 v[86:89], v[172:175], v[206:209], v[86:89]
	v_mfma_f32_16x16x32_bf16 v[82:85], v[180:183], v[206:209], v[82:85]
	v_mfma_f32_16x16x32_bf16 v[70:73], v[172:175], v[214:217], v[70:73]
	v_mfma_f32_16x16x32_bf16 v[66:69], v[180:183], v[214:217], v[66:69]
	s_barrier
	s_setprio 0
	s_add_u32 s44, s44, 0x80
	s_addc_u32 s45, s45, 0
	s_add_i32 m0, s48, 0x18000
	ds_read_b128 v[184:187], v158 offset:49152
	ds_read_b128 v[188:191], v158 offset:50176
	ds_read_b128 v[192:195], v158 offset:51200
	ds_read_b128 v[198:201], v158 offset:52224
	ds_read_b128 v[202:205], v158 offset:53248
	ds_read_b128 v[206:209], v158 offset:54272
	ds_read_b128 v[210:213], v158 offset:55296
	ds_read_b128 v[214:217], v158 offset:56320
	global_load_lds_dwordx4 v132, s[44:45]
	s_add_i32 m0, s48, 0x1a000
	s_add_u32 s46, s46, 0xffc00080
	global_load_lds_dwordx4 v136, s[44:45]
	s_addc_u32 s47, s47, -1
	s_add_u32 s44, s44, 0x400000
	s_addc_u32 s45, s45, 0
	s_add_i32 m0, s48, 0x1c000
	s_nop 0
	global_load_lds_dwordx4 v132, s[44:45]
	s_add_i32 m0, s48, 0x1e000
	s_nop 0
	global_load_lds_dwordx4 v136, s[44:45]
	s_mov_b32 m0, s53
	s_nop 0
	global_load_lds_dwordx4 v130, s[46:47]
	s_mov_b32 m0, s54
	s_nop 0
	global_load_lds_dwordx4 v134, s[46:47]
	s_waitcnt vmcnt(8)
	s_waitcnt lgkmcnt(0)
	s_setprio 1
	s_barrier
	v_mfma_f32_16x16x32_bf16 v[62:65], v[146:149], v[184:187], v[62:65]
	v_mfma_f32_16x16x32_bf16 v[58:61], v[160:163], v[184:187], v[58:61]
	v_mfma_f32_16x16x32_bf16 v[46:49], v[146:149], v[192:195], v[46:49]
	v_mfma_f32_16x16x32_bf16 v[42:45], v[160:163], v[192:195], v[42:45]
	v_mfma_f32_16x16x32_bf16 v[30:33], v[146:149], v[202:205], v[30:33]
	v_mfma_f32_16x16x32_bf16 v[26:29], v[160:163], v[202:205], v[26:29]
	v_mfma_f32_16x16x32_bf16 v[14:17], v[146:149], v[210:213], v[14:17]
	v_mfma_f32_16x16x32_bf16 v[10:13], v[160:163], v[210:213], v[10:13]
	v_mfma_f32_16x16x32_bf16 v[62:65], v[150:153], v[188:191], v[62:65]
	v_mfma_f32_16x16x32_bf16 v[58:61], v[164:167], v[188:191], v[58:61]
	v_mfma_f32_16x16x32_bf16 v[46:49], v[150:153], v[198:201], v[46:49]
	v_mfma_f32_16x16x32_bf16 v[42:45], v[164:167], v[198:201], v[42:45]
	v_mfma_f32_16x16x32_bf16 v[30:33], v[150:153], v[206:209], v[30:33]
	v_mfma_f32_16x16x32_bf16 v[26:29], v[164:167], v[206:209], v[26:29]
	v_mfma_f32_16x16x32_bf16 v[14:17], v[150:153], v[214:217], v[14:17]
	v_mfma_f32_16x16x32_bf16 v[10:13], v[164:167], v[214:217], v[10:13]
	v_mfma_f32_16x16x32_bf16 v[54:57], v[168:171], v[184:187], v[54:57]
	v_mfma_f32_16x16x32_bf16 v[50:53], v[176:179], v[184:187], v[50:53]
	v_mfma_f32_16x16x32_bf16 v[38:41], v[168:171], v[192:195], v[38:41]
	v_mfma_f32_16x16x32_bf16 v[34:37], v[176:179], v[192:195], v[34:37]
	v_mfma_f32_16x16x32_bf16 v[22:25], v[168:171], v[202:205], v[22:25]
	v_mfma_f32_16x16x32_bf16 v[18:21], v[176:179], v[202:205], v[18:21]
	v_mfma_f32_16x16x32_bf16 v[6:9], v[168:171], v[210:213], v[6:9]
	v_mfma_f32_16x16x32_bf16 v[2:5], v[176:179], v[210:213], v[2:5]
	v_mfma_f32_16x16x32_bf16 v[54:57], v[172:175], v[188:191], v[54:57]
	v_mfma_f32_16x16x32_bf16 v[50:53], v[180:183], v[188:191], v[50:53]
	v_mfma_f32_16x16x32_bf16 v[38:41], v[172:175], v[198:201], v[38:41]
	v_mfma_f32_16x16x32_bf16 v[34:37], v[180:183], v[198:201], v[34:37]
	v_mfma_f32_16x16x32_bf16 v[22:25], v[172:175], v[206:209], v[22:25]
	v_mfma_f32_16x16x32_bf16 v[18:21], v[180:183], v[206:209], v[18:21]
	v_mfma_f32_16x16x32_bf16 v[6:9], v[172:175], v[214:217], v[6:9]
	v_mfma_f32_16x16x32_bf16 v[2:5], v[180:183], v[214:217], v[2:5]
	s_barrier
	s_setprio 0
	s_add_i32 s67, s67, 2
	s_add_u32 s42, s42, 0x100
	s_addc_u32 s43, s43, 0
	s_add_u32 s65, s65, 0x100
	s_addc_u32 s66, s66, 0
	s_cmpk_gt_u32 s67, 0xfd
